# barrier-leaders-nonreturning-TOP-add-everyone-polls-TOP
# baseline (speedup 1.0000x reference)
.Lsbar:
	v_readlane_b32 s99, v242, 11
	v_readlane_b32 s100, v242, 30
	s_add_u32 s101, s98, 1
	s_nop 0
	v_mov_b32_e32 v244, s99
	ds_read_b32 v245, v244
	ds_read_b32 v246, v244 offset:4
	s_lshl_b32 s100, s100, 8
	s_add_u32 s100, s100, 0x1400
	v_mov_b32_e32 v247, s100
	v_mov_b32_e32 v248, 1
	global_atomic_add v249, v247, v248, s[70:71] sc0
	buffer_inv sc1
	s_waitcnt lgkmcnt(0)
	v_mul_lo_u32 v245, v245, s101
	v_mul_lo_u32 v246, v246, s101
	v_mov_b32_e32 v250, 0x3500
	v_mov_b32_e32 v251, s98
	s_mov_b32 s99, 0
	s_waitcnt vmcnt(0)
	v_add_u32_e32 v249, 1, v249
	v_cmp_eq_u32_e32 vcc, v249, v245
	s_cbranch_vccz .Lsbar_nl
	buffer_wbl2 sc1
	s_waitcnt vmcnt(0)
	v_mov_b32_e32 v247, 0x3400
	global_atomic_add v247, v248, s[70:71]
.Lsbar_nl:
.Lsbar_poll:
	v_mov_b32_e32 v250, 0x3400
.Lsbar_pl:
	global_load_dword v252, v250, s[70:71] sc1
	s_waitcnt vmcnt(0)
	v_cmp_ge_u32_e32 vcc, v252, v246
	s_cbranch_vccnz .Lsbar_acq
	s_sleep 1
	s_add_u32 s99, s99, 1
	s_cmp_lt_u32 s99, 0x100000
	s_cbranch_scc1 .Lsbar_pl
